# v60 + P9 slot header: wave-uniform conditional complex multiplies as scalar branches instead of compute-and-select
# speedup vs baseline: 1.0001x; 1.0001x over previous
; __device__ __forceinline__ f32x2 s5_carry(const f32x2 pre, const f32x2 (&qe)[3], const f32x4 ap, int c) {
;     const int q = c / 17, k = c - 17 * q;
;     if (q == 0) return pre;
;     float A1r = ap.z, A1i = ap.w;
;     float A2r = A1r, A2i = A1i; cmul(A2r, A2i, A1r, A1i);
;     float A4r = A2r, A4i = A2i; cmul(A4r, A4i, A2r, A2i);
;     float A8r = A4r, A8i = A4i; cmul(A8r, A8i, A4r, A4i);
;     float A16r = A8r, A16i = A8i; cmul(A16r, A16i, A8r, A8i);
;     float A17r = A16r, A17i = A16i; cmul(A17r, A17i, A1r, A1i);
;     float sr = qe[0].x, si = qe[0].y;
;     if (q >= 2) { cmul(sr, si, A17r, A17i); sr += qe[1].x; si += qe[1].y; }
;     if (q >= 3) { cmul(sr, si, A17r, A17i); sr += qe[2].x; si += qe[2].y; }
;     if (k & 1) cmul(sr, si, A1r, A1i);
;     if (k & 2) cmul(sr, si, A2r, A2i);
;     if (k & 4) cmul(sr, si, A4r, A4i);
;     if (k & 8) cmul(sr, si, A8r, A8i);
;     if (k & 16) cmul(sr, si, A16r, A16i);
;     return (f32x2){pre.x + sr, pre.y + si};
.LBB0_756:
	s_and_b32 s24, s5, 63
	s_cmp_lt_u32 s24, 13
	s_waitcnt vmcnt(12)
	v_mov_b64_e32 v[44:45], v[100:101]
	s_cbranch_scc1 .LBB0_758
	s_add_i32 s25, s24, 4
	s_mul_i32 s36, s25, 0x79
	s_bfe_u32 s36, s36, 0x5000b
	s_mul_i32 s36, s36, 17
	s_sub_i32 s25, s25, s36
	s_waitcnt vmcnt(5)
	v_pk_mul_f32 v[44:45], v[122:123], v[98:99] op_sel:[0,1] op_sel_hi:[1,0]
	s_and_b32 s36, s25, 0xff
	v_pk_fma_f32 v[46:47], v[160:161], v[98:99], v[44:45] neg_lo:[0,0,1] neg_hi:[0,0,1]
	v_pk_fma_f32 v[44:45], v[160:161], v[98:99], v[44:45]
	s_cmp_gt_u32 s24, 29
	v_mov_b32_e32 v47, v45
	v_pk_add_f32 v[44:45], v[96:97], v[46:47]
	s_cselect_b64 vcc, -1, 0
	v_cndmask_b32_e32 v45, v99, v45, vcc
	v_cndmask_b32_e32 v44, v98, v44, vcc
	v_pk_mul_f32 v[46:47], v[162:163], v[44:45]
	v_pk_mul_f32 v[48:49], v[124:125], v[44:45]
	s_cmp_gt_u32 s24, 46
	v_sub_f32_e32 v46, v46, v47
	v_add_f32_e32 v47, v48, v49
	v_add_f32_e32 v47, v184, v47
	s_cselect_b64 vcc, -1, 0
	v_add_f32_e32 v46, v183, v46
	v_cndmask_b32_e32 v45, v45, v47, vcc
	v_cndmask_b32_e32 v44, v44, v46, vcc
	s_bitcmp0_b32 s25, 0
	s_cbranch_scc1 .Lp9c_0
	v_mul_f32_e32 v47, v18, v45
	v_mul_f32_e32 v46, v19, v45
	v_fmac_f32_e32 v47, v19, v44
	v_fma_f32 v46, v18, v44, -v46
	v_mov_b32_e32 v45, v47
	v_mov_b32_e32 v44, v46
.Lp9c_0:
	s_bitcmp0_b32 s25, 1
	s_cbranch_scc1 .Lp9c_1
	v_mul_f32_e32 v47, v105, v45
	v_mul_f32_e32 v46, v102, v45
	v_fmac_f32_e32 v47, v102, v44
	v_fma_f32 v46, v105, v44, -v46
	v_mov_b32_e32 v45, v47
	v_mov_b32_e32 v44, v46
.Lp9c_1:
	s_bitcmp0_b32 s25, 2
	s_cbranch_scc1 .Lp9c_2
	v_mul_f32_e32 v47, v111, v45
	v_mul_f32_e32 v46, v108, v45
	v_fmac_f32_e32 v47, v108, v44
	v_fma_f32 v46, v111, v44, -v46
	v_mov_b32_e32 v45, v47
	v_mov_b32_e32 v44, v46
.Lp9c_2:
	s_bitcmp0_b32 s25, 3
	s_cbranch_scc1 .Lp9c_3
	v_mul_f32_e32 v47, v115, v45
	v_mul_f32_e32 v46, v112, v45
	v_fmac_f32_e32 v47, v112, v44
	v_fma_f32 v46, v115, v44, -v46
	v_mov_b32_e32 v45, v47
	v_mov_b32_e32 v44, v46
.Lp9c_3:
	s_cmp_lt_u32 s36, 16
	s_cbranch_scc1 .Lp9c_4
	v_mul_f32_e32 v46, v120, v45
	v_mul_f32_e32 v47, v118, v45
	v_fma_f32 v46, v118, v44, -v46
	v_fmac_f32_e32 v47, v120, v44
	v_mov_b32_e32 v44, v46
	v_mov_b32_e32 v45, v47
.Lp9c_4:
	v_add_f32_e32 v44, v100, v44
	v_add_f32_e32 v45, v101, v45
.LBB0_758:
	s_cmp_gt_u32 s24, 50
	v_mov_b64_e32 v[46:47], v[106:107]
	s_cbranch_scc1 .LBB0_760
	s_sub_i32 s25, 0x43, s24
	s_mul_i32 s36, s25, 0x79
	s_bfe_u32 s36, s36, 0x5000b
	s_mul_i32 s36, s36, 17
	s_sub_i32 s25, s25, s36
	s_waitcnt vmcnt(2)
	v_pk_mul_f32 v[46:47], v[146:147], v[144:145] op_sel:[0,1] op_sel_hi:[1,0]
	s_and_b32 s36, s25, 0xff
	v_pk_fma_f32 v[48:49], v[156:157], v[144:145], v[46:47] neg_lo:[0,0,1] neg_hi:[0,0,1]
	v_pk_fma_f32 v[46:47], v[156:157], v[144:145], v[46:47]
	s_cmp_lt_u32 s24, 34
	v_mov_b32_e32 v49, v47
	v_pk_add_f32 v[46:47], v[140:141], v[48:49]
	s_cselect_b64 vcc, -1, 0
	v_cndmask_b32_e32 v47, v145, v47, vcc
	v_cndmask_b32_e32 v46, v144, v46, vcc
	v_pk_mul_f32 v[48:49], v[158:159], v[46:47]
	v_pk_mul_f32 v[50:51], v[148:149], v[46:47]
	s_cmp_lt_u32 s24, 17
	v_sub_f32_e32 v48, v48, v49
	v_add_f32_e32 v49, v50, v51
	v_add_f32_e32 v49, v186, v49
	s_cselect_b64 vcc, -1, 0
	v_add_f32_e32 v48, v185, v48
	v_cndmask_b32_e32 v47, v47, v49, vcc
	v_cndmask_b32_e32 v46, v46, v48, vcc
	s_bitcmp0_b32 s25, 0
	s_cbranch_scc1 .Lp9c_5
	v_mul_f32_e32 v49, v38, v47
	v_mul_f32_e32 v48, v39, v47
	v_fmac_f32_e32 v49, v39, v46
	v_fma_f32 v48, v38, v46, -v48
	v_mov_b32_e32 v47, v49
	v_mov_b32_e32 v46, v48
.Lp9c_5:
	s_bitcmp0_b32 s25, 1
	s_cbranch_scc1 .Lp9c_6
	v_mul_f32_e32 v49, v129, v47
	v_mul_f32_e32 v48, v126, v47
	v_fmac_f32_e32 v49, v126, v46
	v_fma_f32 v48, v129, v46, -v48
	v_mov_b32_e32 v47, v49
	v_mov_b32_e32 v46, v48
.Lp9c_6:
	s_bitcmp0_b32 s25, 2
	s_cbranch_scc1 .Lp9c_7
	v_mul_f32_e32 v49, v133, v47
	v_mul_f32_e32 v48, v130, v47
	v_fmac_f32_e32 v49, v130, v46
	v_fma_f32 v48, v133, v46, -v48
	v_mov_b32_e32 v47, v49
	v_mov_b32_e32 v46, v48
.Lp9c_7:
	s_bitcmp0_b32 s25, 3
	s_cbranch_scc1 .Lp9c_8
	v_mul_f32_e32 v49, v137, v47
	v_mul_f32_e32 v48, v134, v47
	v_fmac_f32_e32 v49, v134, v46
	v_fma_f32 v48, v137, v46, -v48
	v_mov_b32_e32 v47, v49
	v_mov_b32_e32 v46, v48
.Lp9c_8:
	s_cmp_lt_u32 s36, 16
	s_cbranch_scc1 .Lp9c_9
	v_mul_f32_e32 v48, v142, v47
	v_mul_f32_e32 v49, v138, v47
	v_fma_f32 v48, v138, v46, -v48
	v_fmac_f32_e32 v49, v142, v46
	v_mov_b32_e32 v46, v48
	v_mov_b32_e32 v47, v49
.Lp9c_9:
	v_add_f32_e32 v46, v106, v46
	v_add_f32_e32 v47, v107, v47
